# layer-1 weight conversion split: 3 items per wave in each FFN-in GEMM tail (WGs 128..255), remaining 4736 items at layer-1 top
# baseline (speedup 1.0000x reference)
.LBB0_57:
	s_andn2_b64 vcc, exec, s[4:5]
	s_cbranch_vccnz .LBB0_78
	v_mov_b32_e32 v0, v179
	v_readlane_b32 s5, v249, 24
	v_readfirstlane_b32 s4, v0
	s_ashr_i32 s4, s4, 6
	s_add_i32 s8, s4, s5
	s_cmpk_gt_i32 s8, 0x2a7f
	s_cbranch_scc1 .LBB0_78
	v_bfe_u32 v18, v0, 5, 1
	v_and_b32_e32 v16, 31, v0
	v_bfe_u32 v20, v0, 3, 3
	v_lshlrev_b32_e32 v0, 3, v0
	s_lshl_b32 s5, s4, 14
	v_and_b32_e32 v26, 56, v0
	v_readlane_b32 s6, v252, 39
	s_add_i32 s5, s5, 0
	v_lshlrev_b32_e32 v14, 2, v16
	v_mul_u32_u24_e32 v1, 0x84, v18
	v_lshlrev_b32_e32 v156, 1, v26
	v_readlane_b32 s7, v252, 40
	v_add3_u32 v19, s5, v14, v1
	v_mov_b32_e32 v15, v157
	v_lshl_add_u64 v[0:1], s[6:7], 0, v[156:157]
	v_readlane_b32 s6, v252, 7
	v_readlane_b32 s7, v252, 8
	v_mul_u32_u24_e32 v2, 0x84, v26
	v_lshlrev_b32_e32 v3, 2, v20
	v_lshl_add_u64 v[4:5], s[6:7], 0, v[156:157]
	v_readlane_b32 s6, v251, 56
	v_readlane_b32 s7, v251, 57
	v_add3_u32 v21, s5, v2, v3
	s_lshl_b32 s5, s4, 1
	v_lshl_add_u64 v[6:7], s[6:7], 0, v[156:157]
	v_readlane_b32 s6, v249, 27
	v_readlane_b32 s7, v249, 28
	s_lshl_b32 s4, s4, 5
	s_mov_b64 s[70:71], s[22:23]
	v_lshl_add_u64 v[8:9], s[6:7], 0, v[14:15]
	v_readlane_b32 s6, v249, 29
	v_readlane_b32 s7, v249, 30
	v_or_b32_e32 v22, 8, v20
	v_or_b32_e32 v23, 16, v20
	v_lshl_add_u64 v[10:11], s[6:7], 0, v[14:15]
	v_readlane_b32 s6, v249, 31
	v_readlane_b32 s7, v249, 32
	v_or_b32_e32 v24, 24, v20
	v_lshl_add_u64 v[2:3], s[60:61], 0, v[156:157]
	v_lshl_add_u64 v[12:13], s[6:7], 0, v[14:15]
	v_readlane_b32 s6, v249, 49
	v_readlane_b32 s7, v249, 50
	v_lshlrev_b32_e32 v156, 2, v16
	v_lshlrev_b32_e32 v16, 1, v26
	v_lshl_add_u64 v[14:15], s[6:7], 0, v[14:15]
	v_readlane_b32 s6, v252, 49
	s_add_i32 s9, s6, s5
	v_readlane_b32 s5, v251, 18
	s_add_i32 s10, s5, s4
	v_add_u32_e32 v25, 0x400, v19
	v_add_u32_e32 v26, 0x800, v19
	v_add_u32_e32 v27, 0xc00, v19
	v_add_u32_e32 v28, 0x1000, v19
	v_add_u32_e32 v29, 0x1400, v19
	v_add_u32_e32 v30, 0x1800, v19
	v_add_u32_e32 v31, 0x1c00, v19
	s_movk_i32 s16, 0x7000
	s_mov_b32 s17, 0xf000
	s_mov_b32 s18, 0x16000
	s_mov_b32 s19, 0x25000
	s_mov_b32 s22, 0x2d000
	s_mov_b32 s23, 0x34000
	s_mov_b32 s40, 0x3c000
	s_mov_b32 s41, 0x43000
	s_mov_b32 s46, 0x4b000
	s_mov_b32 s47, 0x52000
	s_mov_b32 s56, 0x5a000
	s_mov_b32 s57, 0x61000
	s_mov_b32 s58, 0x69000
	s_mov_b32 s59, 0x70000
	s_addk_i32 s8, 0xc00
	s_lshl_b32 s9, s8, 1
	s_add_i32 s9, s9, 0x7fffd000
	s_lshl_b32 s10, s8, 5
	s_mov_b32 s100, 0
	s_branch .LBB0_61
.LBB0_60:
	s_addk_i32 s8, 0x800
	s_addk_i32 s9, 0x1000
	s_add_i32 s10, s10, 0x10000
	s_cmp_lg_u32 s100, 0
	s_cbranch_scc1 .LBB0_77
	s_cmpk_lt_i32 s8, 0x1a00
	s_cbranch_scc1 .LBB0_61
	s_mov_b32 s100, 1
	s_addk_i32 s8, 0xc00
	s_addk_i32 s9, 0x1800
	s_add_i32 s10, s10, 0x18000
	s_cmpk_lt_i32 s8, 0x2a80
	s_cbranch_scc0 .LBB0_77

.LBB0_151:
	s_waitcnt vmcnt(0)
	v_readlane_b32 s22, v249, 25
	v_readlane_b32 s50, v253, 21
	v_readlane_b32 s48, v253, 23
	v_readlane_b32 s52, v253, 25
	v_readlane_b32 s23, v249, 26
	v_readlane_b32 s51, v253, 22
	v_readlane_b32 s49, v253, 24
	v_readlane_b32 s53, v253, 26
	s_barrier
	v_readlane_b32 s100, v253, 28
	v_readlane_b32 s101, v249, 24
	s_cmp_eq_u32 s100, 0
	s_cbranch_scc1 .Lcvb_skip
	s_cmpk_lt_u32 s101, 0x400
	s_cbranch_scc1 .Lcvb_skip
	v_writelane_b32 v242, s0, 0
	v_writelane_b32 v242, s1, 1
	v_writelane_b32 v242, s2, 2
	v_writelane_b32 v242, s3, 3
	v_writelane_b32 v242, s4, 4
	v_writelane_b32 v242, s5, 5
	v_writelane_b32 v242, s6, 6
	v_writelane_b32 v242, s7, 7
	v_writelane_b32 v242, s8, 8
	v_writelane_b32 v242, s9, 9
	v_writelane_b32 v242, s10, 10
	v_writelane_b32 v242, s11, 11
	v_writelane_b32 v242, s12, 12
	v_writelane_b32 v242, s13, 13
	v_writelane_b32 v242, s14, 14
	v_writelane_b32 v242, s15, 15
	v_writelane_b32 v242, s16, 16
	v_writelane_b32 v242, s17, 17
	v_writelane_b32 v242, s18, 18
	v_writelane_b32 v242, s19, 19
	v_writelane_b32 v242, s20, 20
	v_writelane_b32 v242, s21, 21
	v_writelane_b32 v242, s22, 22
	v_writelane_b32 v242, s23, 23
	v_writelane_b32 v242, s24, 24
	v_writelane_b32 v242, s25, 25
	v_writelane_b32 v242, s26, 26
	v_writelane_b32 v242, s27, 27
	v_writelane_b32 v242, s28, 28
	v_writelane_b32 v242, s29, 29
	v_writelane_b32 v242, s30, 30
	v_writelane_b32 v242, s31, 31
	v_writelane_b32 v242, s32, 32
	v_writelane_b32 v242, s33, 33
	v_writelane_b32 v242, s34, 34
	v_writelane_b32 v242, s35, 35
	v_writelane_b32 v242, s36, 36
	v_writelane_b32 v242, s37, 37
	v_writelane_b32 v242, s38, 38
	v_writelane_b32 v242, s39, 39
	v_writelane_b32 v242, s40, 40
	v_writelane_b32 v242, s41, 41
	v_writelane_b32 v242, s42, 42
	v_writelane_b32 v242, s43, 43
	v_writelane_b32 v242, s44, 44
	v_writelane_b32 v242, s45, 45
	v_writelane_b32 v242, s46, 46
	v_writelane_b32 v242, s47, 47
	v_writelane_b32 v242, s48, 48
	v_writelane_b32 v242, s49, 49
	v_writelane_b32 v242, s50, 50
	v_writelane_b32 v242, s51, 51
	v_writelane_b32 v242, s52, 52
	v_writelane_b32 v242, s53, 53
	v_writelane_b32 v242, s54, 54
	v_writelane_b32 v242, s55, 55
	v_writelane_b32 v242, s56, 56
	v_writelane_b32 v242, s57, 57
	v_writelane_b32 v242, s58, 58
	v_writelane_b32 v242, s59, 59
	v_writelane_b32 v242, s60, 60
	v_writelane_b32 v242, s61, 61
	v_writelane_b32 v242, s62, 62
	v_writelane_b32 v242, s63, 63
	v_writelane_b32 v243, s64, 0
	v_writelane_b32 v243, s65, 1
	v_writelane_b32 v243, s66, 2
	v_writelane_b32 v243, s67, 3
	v_writelane_b32 v243, s68, 4
	v_writelane_b32 v243, s69, 5
	v_writelane_b32 v243, s70, 6
	v_writelane_b32 v243, s71, 7
	v_writelane_b32 v243, s72, 8
	v_writelane_b32 v243, s73, 9
	v_writelane_b32 v243, s74, 10
	v_writelane_b32 v243, s75, 11
	v_writelane_b32 v243, s76, 12
	v_writelane_b32 v243, s77, 13
	v_writelane_b32 v243, s78, 14
	v_writelane_b32 v243, s79, 15
	v_writelane_b32 v243, s80, 16
	v_writelane_b32 v243, s81, 17
	v_writelane_b32 v243, s82, 18
	v_writelane_b32 v243, s83, 19
	v_writelane_b32 v243, s84, 20
	v_writelane_b32 v243, s85, 21
	v_writelane_b32 v243, s86, 22
	v_writelane_b32 v243, s87, 23
	v_writelane_b32 v243, s88, 24
	v_writelane_b32 v243, s89, 25
	v_writelane_b32 v243, s90, 26
	v_writelane_b32 v243, s91, 27
	v_writelane_b32 v243, s92, 28
	v_writelane_b32 v243, s93, 29
	v_writelane_b32 v243, s94, 30
	v_writelane_b32 v243, s95, 31
	v_writelane_b32 v243, s96, 32
	v_writelane_b32 v243, s97, 33
	v_writelane_b32 v243, s98, 34
	v_writelane_b32 v243, s99, 35
	v_writelane_b32 v243, vcc_lo, 38
	v_writelane_b32 v243, vcc_hi, 39
	v_readlane_b32 s60, v253, 17
	v_readlane_b32 s61, v253, 18
	s_movk_i32 s100, 0x1a00
	s_movk_i32 s101, 0x2600
	v_mov_b32_e32 v0, v179
	v_readlane_b32 s5, v249, 24
	v_readfirstlane_b32 s4, v0
	s_ashr_i32 s4, s4, 6
	s_add_i32 s8, s4, s5
	v_bfe_u32 v18, v0, 5, 1
	v_and_b32_e32 v16, 31, v0
	v_bfe_u32 v20, v0, 3, 3
	v_lshlrev_b32_e32 v0, 3, v0
	s_lshl_b32 s5, s4, 14
	v_and_b32_e32 v26, 56, v0
	v_readlane_b32 s6, v252, 39
	s_add_i32 s5, s5, 0
	v_lshlrev_b32_e32 v14, 2, v16
	v_mul_u32_u24_e32 v1, 0x84, v18
	v_lshlrev_b32_e32 v156, 1, v26
	v_readlane_b32 s7, v252, 40
	v_add3_u32 v19, s5, v14, v1
	v_mov_b32_e32 v15, v157
	v_lshl_add_u64 v[0:1], s[6:7], 0, v[156:157]
	v_readlane_b32 s6, v252, 7
	v_readlane_b32 s7, v252, 8
	v_mul_u32_u24_e32 v2, 0x84, v26
	v_lshlrev_b32_e32 v3, 2, v20
	v_lshl_add_u64 v[4:5], s[6:7], 0, v[156:157]
	v_readlane_b32 s6, v251, 56
	v_readlane_b32 s7, v251, 57
	v_add3_u32 v21, s5, v2, v3
	s_lshl_b32 s5, s4, 1
	v_lshl_add_u64 v[6:7], s[6:7], 0, v[156:157]
	v_readlane_b32 s6, v249, 27
	v_readlane_b32 s7, v249, 28
	s_lshl_b32 s4, s4, 5
	s_mov_b64 s[70:71], s[22:23]
	v_lshl_add_u64 v[8:9], s[6:7], 0, v[14:15]
	v_readlane_b32 s6, v249, 29
	v_readlane_b32 s7, v249, 30
	v_or_b32_e32 v22, 8, v20
	v_or_b32_e32 v23, 16, v20
	v_lshl_add_u64 v[10:11], s[6:7], 0, v[14:15]
	v_readlane_b32 s6, v249, 31
	v_readlane_b32 s7, v249, 32
	v_or_b32_e32 v24, 24, v20
	v_lshl_add_u64 v[2:3], s[60:61], 0, v[156:157]
	v_lshl_add_u64 v[12:13], s[6:7], 0, v[14:15]
	v_readlane_b32 s6, v249, 49
	v_readlane_b32 s7, v249, 50
	v_lshlrev_b32_e32 v156, 2, v16
	v_lshlrev_b32_e32 v16, 1, v26
	v_lshl_add_u64 v[14:15], s[6:7], 0, v[14:15]
	v_readlane_b32 s6, v252, 49
	s_add_i32 s9, s6, s5
	v_readlane_b32 s5, v251, 18
	s_add_i32 s10, s5, s4
	v_add_u32_e32 v25, 0x400, v19
	v_add_u32_e32 v26, 0x800, v19
	v_add_u32_e32 v27, 0xc00, v19
	v_add_u32_e32 v28, 0x1000, v19
	v_add_u32_e32 v29, 0x1400, v19
	v_add_u32_e32 v30, 0x1800, v19
	v_add_u32_e32 v31, 0x1c00, v19
	s_movk_i32 s16, 0x7000
	s_mov_b32 s17, 0xf000
	s_mov_b32 s18, 0x16000
	s_mov_b32 s19, 0x25000
	s_mov_b32 s22, 0x2d000
	s_mov_b32 s23, 0x34000
	s_mov_b32 s40, 0x3c000
	s_mov_b32 s41, 0x43000
	s_mov_b32 s46, 0x4b000
	s_mov_b32 s47, 0x52000
	s_mov_b32 s56, 0x5a000
	s_mov_b32 s57, 0x61000
	s_mov_b32 s58, 0x69000
	s_mov_b32 s59, 0x70000
	s_addk_i32 s8, 0xfc00
	s_add_i32 s8, s8, s100
	s_lshl_b32 s9, s8, 1
	s_add_i32 s9, s9, 0x7fffd000
	s_lshl_b32 s10, s8, 5
	s_cmp_lt_i32 s8, s101
	s_cbranch_scc0 .Lcvb_77
	s_branch .Lcvb_61

.LBB0_1102:
	s_waitcnt vmcnt(0)
	v_readlane_b32 s22, v249, 25
	v_readlane_b32 s50, v253, 21
	v_readlane_b32 s48, v253, 23
	v_readlane_b32 s52, v253, 25
	v_readlane_b32 s23, v249, 26
	v_readlane_b32 s51, v253, 22
	v_readlane_b32 s49, v253, 24
	v_readlane_b32 s53, v253, 26
	s_barrier
	v_readlane_b32 s100, v253, 28
	v_readlane_b32 s101, v249, 24
	s_cmp_lg_u32 s100, 0
	s_cbranch_scc1 .Lcva_skip
	s_cmpk_lt_u32 s101, 0x400
	s_cbranch_scc1 .Lcva_skip
	v_writelane_b32 v242, s0, 0
	v_writelane_b32 v242, s1, 1
	v_writelane_b32 v242, s2, 2
	v_writelane_b32 v242, s3, 3
	v_writelane_b32 v242, s4, 4
	v_writelane_b32 v242, s5, 5
	v_writelane_b32 v242, s6, 6
	v_writelane_b32 v242, s7, 7
	v_writelane_b32 v242, s8, 8
	v_writelane_b32 v242, s9, 9
	v_writelane_b32 v242, s10, 10
	v_writelane_b32 v242, s11, 11
	v_writelane_b32 v242, s12, 12
	v_writelane_b32 v242, s13, 13
	v_writelane_b32 v242, s14, 14
	v_writelane_b32 v242, s15, 15
	v_writelane_b32 v242, s16, 16
	v_writelane_b32 v242, s17, 17
	v_writelane_b32 v242, s18, 18
	v_writelane_b32 v242, s19, 19
	v_writelane_b32 v242, s20, 20
	v_writelane_b32 v242, s21, 21
	v_writelane_b32 v242, s22, 22
	v_writelane_b32 v242, s23, 23
	v_writelane_b32 v242, s24, 24
	v_writelane_b32 v242, s25, 25
	v_writelane_b32 v242, s26, 26
	v_writelane_b32 v242, s27, 27
	v_writelane_b32 v242, s28, 28
	v_writelane_b32 v242, s29, 29
	v_writelane_b32 v242, s30, 30
	v_writelane_b32 v242, s31, 31
	v_writelane_b32 v242, s32, 32
	v_writelane_b32 v242, s33, 33
	v_writelane_b32 v242, s34, 34
	v_writelane_b32 v242, s35, 35
	v_writelane_b32 v242, s36, 36
	v_writelane_b32 v242, s37, 37
	v_writelane_b32 v242, s38, 38
	v_writelane_b32 v242, s39, 39
	v_writelane_b32 v242, s40, 40
	v_writelane_b32 v242, s41, 41
	v_writelane_b32 v242, s42, 42
	v_writelane_b32 v242, s43, 43
	v_writelane_b32 v242, s44, 44
	v_writelane_b32 v242, s45, 45
	v_writelane_b32 v242, s46, 46
	v_writelane_b32 v242, s47, 47
	v_writelane_b32 v242, s48, 48
	v_writelane_b32 v242, s49, 49
	v_writelane_b32 v242, s50, 50
	v_writelane_b32 v242, s51, 51
	v_writelane_b32 v242, s52, 52
	v_writelane_b32 v242, s53, 53
	v_writelane_b32 v242, s54, 54
	v_writelane_b32 v242, s55, 55
	v_writelane_b32 v242, s56, 56
	v_writelane_b32 v242, s57, 57
	v_writelane_b32 v242, s58, 58
	v_writelane_b32 v242, s59, 59
	v_writelane_b32 v242, s60, 60
	v_writelane_b32 v242, s61, 61
	v_writelane_b32 v242, s62, 62
	v_writelane_b32 v242, s63, 63
	v_writelane_b32 v243, s64, 0
	v_writelane_b32 v243, s65, 1
	v_writelane_b32 v243, s66, 2
	v_writelane_b32 v243, s67, 3
	v_writelane_b32 v243, s68, 4
	v_writelane_b32 v243, s69, 5
	v_writelane_b32 v243, s70, 6
	v_writelane_b32 v243, s71, 7
	v_writelane_b32 v243, s72, 8
	v_writelane_b32 v243, s73, 9
	v_writelane_b32 v243, s74, 10
	v_writelane_b32 v243, s75, 11
	v_writelane_b32 v243, s76, 12
	v_writelane_b32 v243, s77, 13
	v_writelane_b32 v243, s78, 14
	v_writelane_b32 v243, s79, 15
	v_writelane_b32 v243, s80, 16
	v_writelane_b32 v243, s81, 17
	v_writelane_b32 v243, s82, 18
	v_writelane_b32 v243, s83, 19
	v_writelane_b32 v243, s84, 20
	v_writelane_b32 v243, s85, 21
	v_writelane_b32 v243, s86, 22
	v_writelane_b32 v243, s87, 23
	v_writelane_b32 v243, s88, 24
	v_writelane_b32 v243, s89, 25
	v_writelane_b32 v243, s90, 26
	v_writelane_b32 v243, s91, 27
	v_writelane_b32 v243, s92, 28
	v_writelane_b32 v243, s93, 29
	v_writelane_b32 v243, s94, 30
	v_writelane_b32 v243, s95, 31
	v_writelane_b32 v243, s96, 32
	v_writelane_b32 v243, s97, 33
	v_writelane_b32 v243, s98, 34
	v_writelane_b32 v243, s99, 35
	v_writelane_b32 v243, vcc_lo, 38
	v_writelane_b32 v243, vcc_hi, 39
	v_readlane_b32 s60, v253, 17
	v_readlane_b32 s61, v253, 18
	s_mov_b32 s100, 0
	s_movk_i32 s101, 0xc00
	v_mov_b32_e32 v0, v179
	v_readlane_b32 s5, v249, 24
	v_readfirstlane_b32 s4, v0
	s_ashr_i32 s4, s4, 6
	s_add_i32 s8, s4, s5
	v_bfe_u32 v18, v0, 5, 1
	v_and_b32_e32 v16, 31, v0
	v_bfe_u32 v20, v0, 3, 3
	v_lshlrev_b32_e32 v0, 3, v0
	s_lshl_b32 s5, s4, 14
	v_and_b32_e32 v26, 56, v0
	v_readlane_b32 s6, v252, 39
	s_add_i32 s5, s5, 0
	v_lshlrev_b32_e32 v14, 2, v16
	v_mul_u32_u24_e32 v1, 0x84, v18
	v_lshlrev_b32_e32 v156, 1, v26
	v_readlane_b32 s7, v252, 40
	v_add3_u32 v19, s5, v14, v1
	v_mov_b32_e32 v15, v157
	v_lshl_add_u64 v[0:1], s[6:7], 0, v[156:157]
	v_readlane_b32 s6, v252, 7
	v_readlane_b32 s7, v252, 8
	v_mul_u32_u24_e32 v2, 0x84, v26
	v_lshlrev_b32_e32 v3, 2, v20
	v_lshl_add_u64 v[4:5], s[6:7], 0, v[156:157]
	v_readlane_b32 s6, v251, 56
	v_readlane_b32 s7, v251, 57
	v_add3_u32 v21, s5, v2, v3
	s_lshl_b32 s5, s4, 1
	v_lshl_add_u64 v[6:7], s[6:7], 0, v[156:157]
	v_readlane_b32 s6, v249, 27
	v_readlane_b32 s7, v249, 28
	s_lshl_b32 s4, s4, 5
	s_mov_b64 s[70:71], s[22:23]
	v_lshl_add_u64 v[8:9], s[6:7], 0, v[14:15]
	v_readlane_b32 s6, v249, 29
	v_readlane_b32 s7, v249, 30
	v_or_b32_e32 v22, 8, v20
	v_or_b32_e32 v23, 16, v20
	v_lshl_add_u64 v[10:11], s[6:7], 0, v[14:15]
	v_readlane_b32 s6, v249, 31
	v_readlane_b32 s7, v249, 32
	v_or_b32_e32 v24, 24, v20
	v_lshl_add_u64 v[2:3], s[60:61], 0, v[156:157]
	v_lshl_add_u64 v[12:13], s[6:7], 0, v[14:15]
	v_readlane_b32 s6, v249, 49
	v_readlane_b32 s7, v249, 50
	v_lshlrev_b32_e32 v156, 2, v16
	v_lshlrev_b32_e32 v16, 1, v26
	v_lshl_add_u64 v[14:15], s[6:7], 0, v[14:15]
	v_readlane_b32 s6, v252, 49
	s_add_i32 s9, s6, s5
	v_readlane_b32 s5, v251, 18
	s_add_i32 s10, s5, s4
	v_add_u32_e32 v25, 0x400, v19
	v_add_u32_e32 v26, 0x800, v19
	v_add_u32_e32 v27, 0xc00, v19
	v_add_u32_e32 v28, 0x1000, v19
	v_add_u32_e32 v29, 0x1400, v19
	v_add_u32_e32 v30, 0x1800, v19
	v_add_u32_e32 v31, 0x1c00, v19
	s_movk_i32 s16, 0x7000
	s_mov_b32 s17, 0xf000
	s_mov_b32 s18, 0x16000
	s_mov_b32 s19, 0x25000
	s_mov_b32 s22, 0x2d000
	s_mov_b32 s23, 0x34000
	s_mov_b32 s40, 0x3c000
	s_mov_b32 s41, 0x43000
	s_mov_b32 s46, 0x4b000
	s_mov_b32 s47, 0x52000
	s_mov_b32 s56, 0x5a000
	s_mov_b32 s57, 0x61000
	s_mov_b32 s58, 0x69000
	s_mov_b32 s59, 0x70000
	s_addk_i32 s8, 0xfc00
	s_add_i32 s8, s8, s100
	s_lshl_b32 s9, s8, 1
	s_add_i32 s9, s9, 0x7fffd000
	s_lshl_b32 s10, s8, 5
	s_cmp_lt_i32 s8, s101
	s_cbranch_scc0 .Lcva_77
	s_branch .Lcva_61
